# row-panel gates polled by wave 1 (thread 64) so poll + acquire overlap wave 0's barrier-arrive bookkeeping
# baseline (speedup 1.0000x reference)
.LBB0_29:
	v_cmp_eq_u32_e32 vcc, 64, v234
	s_and_saveexec_b64 s[8:9], vcc
	s_cbranch_execz .LBB0_58
	s_lshl_b32 s10, s86, 4
	s_andn2_b32 s10, s10, 63
	s_ashr_i32 s11, s10, 31
	s_lshl_b64 s[10:11], s[10:11], 2
	s_add_u32 s10, s0, s10
	s_addc_u32 s11, s1, s11
	v_mov_b32_e32 v1, 0x10000
	global_load_dword v1, v1, s[10:11] sc1
	s_add_u32 s10, s10, 0x10000
	s_addc_u32 s11, s11, 0
	s_waitcnt vmcnt(0)
	v_cmp_lt_u32_e32 vcc, 3, v1
	s_cbranch_vccnz .LBB0_41
	s_add_u32 s12, s0, 0x1200
	s_addc_u32 s13, s1, 0
	s_mov_b32 s20, 1
	s_branch .LBB0_33

.LBB0_254:
	s_and_b64 vcc, exec, s[4:5]
	s_cbranch_vccz .LBB0_327
	v_readlane_b32 s4, v254, 49
	v_readlane_b32 s5, v254, 50
	s_load_dword s4, s[4:5], 0x88
	s_waitcnt lgkmcnt(0)
	s_cmp_gt_i32 s74, s4
	s_cselect_b64 s[4:5], -1, 0
	s_cmp_gt_i32 s29, 0
	s_cselect_b64 s[6:7], -1, 0
	s_cmpk_eq_i32 s98, 0x100
	s_cselect_b64 s[8:9], -1, 0
	s_or_b64 s[6:7], s[6:7], s[8:9]
	s_and_b64 s[6:7], s[4:5], s[6:7]
	s_cmp_lt_u32 s17, 2
	s_cselect_b64 s[4:5], -1, 0
	s_and_b64 s[4:5], s[6:7], s[4:5]
	s_andn2_b64 vcc, exec, s[4:5]
	s_cbranch_vccnz .LBB0_273
	v_cmp_eq_u32_e32 vcc, 64, v234
	s_and_saveexec_b64 s[4:5], vcc
	s_cbranch_execz .LBB0_272
	v_readlane_b32 s8, v254, 47
	v_readlane_b32 s9, v254, 48
	s_mov_b32 s10, s8
	s_lshl_b32 s8, s8, 3
	s_and_b32 s8, s8, 56
	s_bfe_u32 s9, s10, 0x30003
	s_or_b32 s8, s8, s9
	s_lshl_b32 s8, s8, 8
	s_add_u32 s8, s0, s8
	s_addc_u32 s9, s1, 0
	v_mov_b32_e32 v1, 0x1c000
	global_load_dword v1, v1, s[8:9] sc1
	s_add_u32 s8, s8, 0x1c000
	s_addc_u32 s9, s9, 0
	s_waitcnt vmcnt(0)
	v_cmp_lt_u32_e32 vcc, 3, v1
	s_cbranch_vccnz .LBB0_268
	s_add_u32 s10, s0, 0x1200
	s_addc_u32 s11, s1, 0
	s_mov_b32 s18, 1
	s_branch .LBB0_260

.LBB0_333:
	s_cmp_gt_i32 s74, 5
	s_cselect_b64 s[4:5], -1, 0
	s_andn2_b64 vcc, exec, s[10:11]
	s_cbranch_vccnz .LBB0_354
	v_cmp_eq_u32_e32 vcc, 64, v234
	s_and_saveexec_b64 s[6:7], vcc
	s_cbranch_execz .LBB0_353
	s_and_b64 s[12:13], s[4:5], exec
	s_movk_i32 s12, 0x4000
	s_cselect_b32 s12, 0x14000, s12
	s_add_u32 s12, s0, s12
	v_readlane_b32 s14, v254, 47
	s_addc_u32 s13, s1, 0
	v_readlane_b32 s15, v254, 48
	s_mov_b32 s16, s14
	s_lshl_b32 s14, s14, 3
	s_and_b32 s14, s14, 56
	s_bfe_u32 s15, s16, 0x30003
	s_or_b32 s14, s14, s15
	s_lshl_b32 s14, s14, 8
	s_add_u32 s12, s12, s14
	s_addc_u32 s13, s13, 0
	v_mov_b32_e32 v1, 0x10000
	global_load_dword v1, v1, s[12:13] sc1
	s_add_u32 s12, s12, 0x10000
	s_addc_u32 s13, s13, 0
	s_waitcnt vmcnt(0)
	v_cmp_lt_u32_e32 vcc, 3, v1
	s_cbranch_vccnz .LBB0_349
	s_add_u32 s14, s0, 0x1200
	s_addc_u32 s15, s1, 0
	s_mov_b32 s22, 1
	s_branch .LBB0_338

.LBB0_399:
	s_and_b64 s[4:5], s[16:17], s[24:25]
	s_andn2_b64 vcc, exec, s[4:5]
	s_mov_b64 s[4:5], -1
	s_cbranch_vccz .LBB0_420
	s_mov_b64 s[4:5], 0
	s_and_b64 vcc, exec, s[24:25]
	s_cbranch_vccz .LBB0_420
	v_cmp_eq_u32_e32 vcc, 64, v234
	s_and_saveexec_b64 s[8:9], vcc
	s_cbranch_execz .LBB0_419
	s_and_b64 s[12:13], s[20:21], exec
	s_mov_b32 s12, 0x9000
	s_cselect_b32 s14, s12, 0xb000
	s_and_b64 s[12:13], exec, s[18:19]
	s_cselect_b32 s12, 0x7000, s14
	s_lshl_b32 s12, s12, 2
	s_add_u32 s12, s0, s12
	s_addc_u32 s13, s1, 0
	s_lshl_b32 s14, s36, 3
	s_and_b32 s14, s14, 56
	s_bfe_u32 s15, s36, 0x30003
	s_or_b32 s14, s14, s15
	s_lshl_b32 s14, s14, 8
	s_add_u32 s12, s12, s14
	s_addc_u32 s13, s13, 0
	v_mov_b32_e32 v1, 0x10000
	global_load_dword v1, v1, s[12:13] sc1
	s_add_u32 s12, s12, 0x10000
	s_addc_u32 s13, s13, 0
	s_waitcnt vmcnt(0)
	v_cmp_lt_u32_e32 vcc, 3, v1
	s_cbranch_vccnz .LBB0_415
	s_add_u32 s14, s0, 0x1200
	s_addc_u32 s15, s1, 0
	s_mov_b32 s34, 1
	s_branch .LBB0_405
